# previous + full barrier: waiting workgroups poll the global generation word directly (one atomic+poll round trip fewer per full barrier)
# speedup vs baseline: 1.0254x; 1.0028x over previous
; __device__ __forceinline__ unsigned xb_ld(unsigned* p)              { return __hip_atomic_load(p, __ATOMIC_RELAXED, __HIP_MEMORY_SCOPE_AGENT); }
; __device__ __forceinline__ unsigned xb_add(unsigned* p, unsigned v) { return __hip_atomic_fetch_add(p, v, __ATOMIC_RELAXED, __HIP_MEMORY_SCOPE_AGENT); }
; #define XB_SPIN(cond, bar) do { unsigned _sp = 0; while (cond) { __builtin_amdgcn_s_sleep(1); \
;     if ((++_sp & 255u) == 0u) { if (xb_ld(&(bar)[XB_TMO])) break; if (_sp > XB_SPIN_CAP) { atomicAdd(&(bar)[XB_TMO], 1u); break; } } } } while (0)
; __device__ __forceinline__ void xcd_barrier(const XcdBarrier& b) {
;     ...
;         const unsigned old = xb_add(&bar[XB_XSUB(b.x)], 1u);
;         const unsigned gen = old / nloc;
;         if (old + 1u == (gen + 1u) * nloc) {
;             __builtin_amdgcn_fence(__ATOMIC_RELEASE, "agent");
;             asm volatile("s_waitcnt vmcnt(0)" ::: "memory");
;             const unsigned og = xb_add(&bar[XB_TOP], 1u);
;             const unsigned tg = og / nx;
;             if (og + 1u == (tg + 1u) * nx) xb_add(&bar[XB_TOPGEN], 1u);
;             else XB_SPIN(xb_ld(&bar[XB_TOPGEN]) == tg, bar);
;             __builtin_amdgcn_fence(__ATOMIC_ACQUIRE, "agent");
;             xb_add(&bar[XB_XGEN(b.x)], 1u);
;             asm volatile("s_waitcnt vmcnt(0)" ::: "memory");
;         } else {
;             XB_SPIN(xb_ld(&bar[XB_XGEN(b.x)]) == gen, bar);
.LBB0_452:
	s_or_b64 exec, exec, s[34:35]
	v_cvt_f32_u32_e32 v5, v3
	s_waitcnt vmcnt(0)
	v_readfirstlane_b32 s2, v4
	v_sub_u32_e32 v4, 0, v3
	v_rcp_iflag_f32_e32 v5, v5
	v_add_u32_e32 v6, s2, v1
	v_mul_f32_e32 v5, 0x4f7ffffe, v5
	v_cvt_u32_f32_e32 v5, v5
	v_mul_lo_u32 v1, v4, v5
	v_mul_hi_u32 v1, v5, v1
	v_add_u32_e32 v1, v5, v1
	v_mul_hi_u32 v1, v6, v1
	v_mul_lo_u32 v4, v1, v3
	v_sub_u32_e32 v4, v6, v4
	v_add_u32_e32 v5, 1, v1
	v_cmp_ge_u32_e32 vcc, v4, v3
	s_nop 1
	v_cndmask_b32_e32 v1, v1, v5, vcc
	v_sub_u32_e32 v5, v4, v3
	v_cndmask_b32_e32 v4, v4, v5, vcc
	v_add_u32_e32 v5, 1, v1
	v_cmp_ge_u32_e32 vcc, v4, v3
	v_add_u32_e32 v4, 1, v6
	s_nop 0
	v_cndmask_b32_e32 v1, v1, v5, vcc
	v_mul_lo_u32 v5, v3, v1
	v_add_u32_e32 v3, v5, v3
	v_cmp_ne_u32_e32 vcc, v4, v3
	s_and_saveexec_b64 s[2:3], vcc
	s_xor_b64 s[34:35], exec, s[2:3]
	s_cbranch_execz .LBB0_466
	v_readlane_b32 s2, v254, 20
	v_readlane_b32 s3, v254, 21
	s_waitcnt lgkmcnt(0)
	s_nop 3
	global_load_dword v0, v2, s[2:3] sc1
	s_waitcnt vmcnt(0)
	v_cmp_eq_u32_e32 vcc, v0, v1
	s_and_saveexec_b64 s[38:39], vcc
	s_cbranch_execz .LBB0_465
	s_mov_b32 s2, 1
	s_mov_b64 s[40:41], 0
	s_branch .LBB0_456

; __device__ __forceinline__ unsigned xb_ld(unsigned* p)              { return __hip_atomic_load(p, __ATOMIC_RELAXED, __HIP_MEMORY_SCOPE_AGENT); }
; #define XB_SPIN(cond, bar) do { unsigned _sp = 0; while (cond) { __builtin_amdgcn_s_sleep(1); \
;     if ((++_sp & 255u) == 0u) { if (xb_ld(&(bar)[XB_TMO])) break; if (_sp > XB_SPIN_CAP) { atomicAdd(&(bar)[XB_TMO], 1u); break; } } } } while (0)
; __device__ __forceinline__ void xcd_barrier(const XcdBarrier& b) {
;     ...
;             XB_SPIN(xb_ld(&bar[XB_XGEN(b.x)]) == gen, bar);
.LBB0_460:
	v_readlane_b32 s22, v254, 20
	v_readlane_b32 s23, v254, 21
	s_add_i32 s2, s2, 1
	s_mov_b64 s[46:47], -1
	s_nop 2
	global_load_dword v0, v2, s[22:23] sc1
	s_waitcnt vmcnt(0)
	v_cmp_ne_u32_e32 vcc, v0, v1
	s_orn2_b64 s[44:45], vcc, exec
	s_branch .LBB0_455
